# la_unit: every 16-row log-decay fragment shared by two waves (4 of 8 column blocks each) on all 32 ranks instead of whole fragments on ranks 0-16; plus fast group barrier, pipelined la loads, P0 loads
# speedup vs baseline: 1.0156x; 1.0113x over previous
; #define LAS __attribute__((address_space(3)))
; DI void la_unit(const bf16* __restrict__ XB, const bf16* __restrict__ W16, const float* SS, const float* __restrict__ wa2, const float* __restrict__ ba, float* __restrict__ LA, LAS float* scr, int row0, int lane) {
;     const int fr = lane & 15, fq = lane >> 4;
;     const bf16* ap = XB + (size_t)(row0 + fr) * DM + 8 * fq; const bf16* bp = W16 + (size_t)fr * DM + 8 * fq;
; __global__ void __launch_bounds__(NTHREADS, 2) hybrid_fwd(Args Aval) {
;     ...
;                 {   const int f = rank * NWAVES + wave;
;                     if (f < 136) la_unit((const bf16*)(ws + WS_XB), W + (size_t)3072 * DM, (const float*)(ws + WS_SSQ), A->in[I_GLAWA2] + (size_t)j * 16 * 512, A->in[I_GLABA] + j * 512, (float*)(ws + WS_LA), (LAS float*)(lds + wave * 1024),
;                                          f < 128 ? 2048 * grp + 16 * f : MP + 128 * grp + 16 * (f - 128), lane); }
.LBB0_236:
	s_ashr_i32 s5, s55, 3
	s_lshl_b32 s4, s5, 3
	s_add_i32 s4, s4, s3
	s_sub_i32 s6, s5, 24
	s_mul_i32 s12, s6, 6
	s_add_i32 s12, s12, s3
	s_addk_i32 s12, 0xbe
	s_cmp_gt_i32 s5, 23
	s_cselect_b32 s4, s12, s4
	s_and_b32 s100, s4, 1
	s_lshl_b32 s100, s100, 2
	s_add_i32 s101, s100, 4
	s_lshr_b32 s4, s4, 1
	s_lshl_b32 s6, s6, 1
	s_add_i32 s6, s6, s3
	s_addk_i32 s6, 0x78
	s_cmp_gt_i32 s5, 23
	s_cselect_b32 s12, 1, 0
	s_cmp_lt_u32 s3, 2
	s_cselect_b32 s5, 1, 0
	s_and_b32 s12, s12, s5
	s_cselect_b32 s4, s6, s4
	s_cselect_b32 s100, 0, s100
	s_cselect_b32 s101, 8, s101
	s_cmpk_gt_i32 s4, 0x87
	s_cbranch_scc1 .LBB0_248
	s_lshl_b32 s6, s4, 4
	s_cmpk_gt_i32 s4, 0x7f
	s_mov_b64 s[4:5], -1
	s_cbranch_scc0 .LBB0_239
	s_lshl_b32 s4, s54, 7
	s_add_i32 s4, s6, s4
	s_add_i32 s12, s4, 0x3800
	s_mov_b64 s[4:5], 0

; #define LAS __attribute__((address_space(3)))
; DI float xsum16(float v) { const unsigned u = __float_as_uint(v); const u32x2p r = __builtin_amdgcn_permlane16_swap(u, u, false, false); return __uint_as_float(r[0]) + __uint_as_float(r[1]); }
; DI float xsum32(float v) { const unsigned u = __float_as_uint(v); const u32x2p r = __builtin_amdgcn_permlane32_swap(u, u, false, false); return __uint_as_float(r[0]) + __uint_as_float(r[1]); }
; #define LDS_WAIT() asm volatile("s_waitcnt lgkmcnt(0)" ::: "memory")
; DI float rs_of_row(const float* SS, int row, int fq) {
;     const f32x4 a = *(const f32x4*)(SS + (size_t)row * 32 + 8 * fq), b = *(const f32x4*)(SS + (size_t)row * 32 + 8 * fq + 4);
;     float s = ((a[0] + a[1]) + (a[2] + a[3])) + ((b[0] + b[1]) + (b[2] + b[3]));
;     s = xsum32(xsum16(s));
;     return __builtin_amdgcn_rsqf(s * (1.0f / 1024.0f) + RMS_EPS);
; }
; DI void la_unit(const bf16* __restrict__ XB, const bf16* __restrict__ W16, const float* SS, const float* __restrict__ wa2, const float* __restrict__ ba, float* __restrict__ LA, LAS float* scr, int row0, int lane) {
;     ...
;     f32x4 acc = (f32x4){0.f, 0.f, 0.f, 0.f};
; #pragma unroll 8
;     for (int k0 = 0; k0 < DM; k0 += 32) acc = __builtin_amdgcn_mfma_f32_16x16x32_bf16(*(const bf16x8*)(bp + k0), *(const bf16x8*)(ap + k0), acc, 0, 0, 0);
;     const float rs = pg8::rs_of_row(SS, row0 + fr, fq);
;     *(LAS f32x4*)(scr + fr * 16 + 4 * fq) = acc * rs;
;     LDS_WAIT(); asm volatile("" ::: "memory");
.LBB0_242:
	global_load_dwordx4 v[50:53], v[12:13], off offset:-256
	global_load_dwordx4 v[114:117], v[10:11], off offset:-256
	global_load_dwordx4 v[54:57], v[12:13], off offset:-192
	global_load_dwordx4 v[118:121], v[10:11], off offset:-192
	global_load_dwordx4 v[58:61], v[12:13], off offset:-128
	global_load_dwordx4 v[122:125], v[10:11], off offset:-128
	global_load_dwordx4 v[62:65], v[12:13], off offset:-64
	global_load_dwordx4 v[126:129], v[10:11], off offset:-64
	global_load_dwordx4 v[66:69], v[12:13], off
	global_load_dwordx4 v[130:133], v[10:11], off
	global_load_dwordx4 v[70:73], v[12:13], off offset:64
	global_load_dwordx4 v[134:137], v[10:11], off offset:64
	global_load_dwordx4 v[74:77], v[12:13], off offset:128
	global_load_dwordx4 v[138:141], v[10:11], off offset:128
	global_load_dwordx4 v[78:81], v[12:13], off offset:192
	global_load_dwordx4 v[142:145], v[10:11], off offset:192
	global_load_dwordx4 v[82:85], v[12:13], off offset:256
	global_load_dwordx4 v[146:149], v[10:11], off offset:256
	global_load_dwordx4 v[86:89], v[12:13], off offset:320
	global_load_dwordx4 v[150:153], v[10:11], off offset:320
	global_load_dwordx4 v[90:93], v[12:13], off offset:384
	global_load_dwordx4 v[170:173], v[10:11], off offset:384
	global_load_dwordx4 v[94:97], v[12:13], off offset:448
	global_load_dwordx4 v[174:177], v[10:11], off offset:448
	global_load_dwordx4 v[98:101], v[12:13], off offset:512
	global_load_dwordx4 v[178:181], v[10:11], off offset:512
	global_load_dwordx4 v[102:105], v[12:13], off offset:576
	global_load_dwordx4 v[182:185], v[10:11], off offset:576
	global_load_dwordx4 v[106:109], v[12:13], off offset:640
	global_load_dwordx4 v[186:189], v[10:11], off offset:640
	global_load_dwordx4 v[110:113], v[12:13], off offset:704
	global_load_dwordx4 v[190:193], v[10:11], off offset:704
	s_addk_i32 s10, 0x200
	v_lshl_add_u64 v[10:11], v[10:11], 0, s[14:15]
	v_lshl_add_u64 v[12:13], v[12:13], 0, s[14:15]
	s_waitcnt vmcnt(30)
	v_mfma_f32_16x16x32_bf16 v[4:7], v[50:53], v[114:117], v[4:7]
	s_waitcnt vmcnt(28)
	v_mfma_f32_16x16x32_bf16 v[4:7], v[54:57], v[118:121], v[4:7]
	s_waitcnt vmcnt(26)
	v_mfma_f32_16x16x32_bf16 v[4:7], v[58:61], v[122:125], v[4:7]
	s_waitcnt vmcnt(24)
	v_mfma_f32_16x16x32_bf16 v[4:7], v[62:65], v[126:129], v[4:7]
	s_waitcnt vmcnt(22)
	v_mfma_f32_16x16x32_bf16 v[4:7], v[66:69], v[130:133], v[4:7]
	s_waitcnt vmcnt(20)
	v_mfma_f32_16x16x32_bf16 v[4:7], v[70:73], v[134:137], v[4:7]
	s_waitcnt vmcnt(18)
	v_mfma_f32_16x16x32_bf16 v[4:7], v[74:77], v[138:141], v[4:7]
	s_waitcnt vmcnt(16)
	v_mfma_f32_16x16x32_bf16 v[4:7], v[78:81], v[142:145], v[4:7]
	s_waitcnt vmcnt(14)
	v_mfma_f32_16x16x32_bf16 v[4:7], v[82:85], v[146:149], v[4:7]
	s_waitcnt vmcnt(12)
	v_mfma_f32_16x16x32_bf16 v[4:7], v[86:89], v[150:153], v[4:7]
	s_waitcnt vmcnt(10)
	v_mfma_f32_16x16x32_bf16 v[4:7], v[90:93], v[170:173], v[4:7]
	s_waitcnt vmcnt(8)
	v_mfma_f32_16x16x32_bf16 v[4:7], v[94:97], v[174:177], v[4:7]
	s_waitcnt vmcnt(6)
	v_mfma_f32_16x16x32_bf16 v[4:7], v[98:101], v[178:181], v[4:7]
	s_waitcnt vmcnt(4)
	v_mfma_f32_16x16x32_bf16 v[4:7], v[102:105], v[182:185], v[4:7]
	s_waitcnt vmcnt(2)
	v_mfma_f32_16x16x32_bf16 v[4:7], v[106:109], v[186:189], v[4:7]
	s_waitcnt vmcnt(0)
	v_mfma_f32_16x16x32_bf16 v[4:7], v[110:113], v[190:193], v[4:7]
	s_cmpk_gt_u32 s10, 0x3df
	s_cbranch_scc0 .LBB0_242
	v_lshlrev_b64 v[8:9], 7, v[8:9]
	v_lshl_add_u64 v[8:9], s[8:9], 0, v[8:9]
	v_mov_b32_e32 v39, v2
	v_lshl_add_u64 v[12:13], v[8:9], 0, v[38:39]
	global_load_dwordx4 v[8:11], v[12:13], off
	s_nop 0
	global_load_dwordx4 v[12:15], v[12:13], off offset:16
	s_lshl_b64 s[8:9], s[94:95], 15
	s_waitcnt lgkmcnt(0)
	s_add_u32 s4, s4, s8
	s_addc_u32 s5, s5, s9
	s_lshl_b32 s34, s94, 9
	s_lshl_b64 s[8:9], s[34:35], 2
	s_add_u32 s6, s6, s8
	s_addc_u32 s7, s7, s9
	s_lshl_b32 s3, s3, 10
	s_add_i32 s3, s3, 0
	v_add3_u32 v3, s3, v3, v49
	s_ashr_i32 s13, s12, 31
	s_lshl_b64 s[8:9], s[12:13], 11
	s_add_u32 s0, s0, s8
	v_mov_b32_e32 v37, v2
	s_addc_u32 s1, s1, s9
	s_lshl_b32 s9, s100, 8
	s_add_u32 s0, s0, s9
	s_addc_u32 s1, s1, 0
	s_mov_b32 s8, s100
	s_waitcnt vmcnt(1)
	v_add_f32_e32 v8, v8, v9
	v_add_f32_e32 v9, v10, v11
	s_waitcnt vmcnt(0)
	v_add_f32_e32 v10, v12, v13
	v_add_f32_e32 v11, v14, v15
	v_add_f32_e32 v8, v8, v9
	v_add_f32_e32 v9, v10, v11
	v_add_f32_e32 v8, v8, v9
	v_mov_b32_e32 v9, v8
	s_nop 1
	v_permlane16_swap_b32_e32 v8, v9
	v_add_f32_e32 v8, v8, v9
	v_mov_b32_e32 v9, v8
	s_nop 1
	v_permlane32_swap_b32_e32 v8, v9
	v_add_f32_e32 v8, v8, v9
	v_fmamk_f32 v8, v8, 0x3a800000, v1
	v_rsq_f32_e32 v8, v8
	s_nop 0
	v_pk_mul_f32 v[6:7], v[6:7], v[8:9] op_sel_hi:[1,0]
	v_pk_mul_f32 v[4:5], v[4:5], v[8:9] op_sel_hi:[1,0]
	ds_write_b128 v3, v[4:7]
	s_waitcnt lgkmcnt(0)
	v_lshl_add_u64 v[4:5], s[0:1], 0, v[36:37]

; #define LAS __attribute__((address_space(3)))
; DI float log_sigmoid_f(float x) { return fminf(x, 0.f) - 0.6931471805599453f * __builtin_amdgcn_logf(1.0f + fexp(-__builtin_fabsf(x))); }
; DI void la_unit(const bf16* __restrict__ XB, const bf16* __restrict__ W16, const float* SS, const float* __restrict__ wa2, const float* __restrict__ ba, float* __restrict__ LA, LAS float* scr, int row0, int lane) {
;     ...
;     for (int nb = 0; nb < 8; ++nb) {
;         float w[16];
; #pragma unroll
;         for (int rk = 0; rk < 16; ++rk) w[rk] = wa2[rk * 512 + 64 * nb + lane];
;         const float bb = ba[64 * nb + lane];
; #pragma unroll 4
;         for (int row = 0; row < 16; ++row) {
;             const f32x4 a0 = *(const LAS f32x4*)(scr + row * 16), a1 = *(const LAS f32x4*)(scr + row * 16 + 4), a2 = *(const LAS f32x4*)(scr + row * 16 + 8), a3 = *(const LAS f32x4*)(scr + row * 16 + 12);
;             float pre = bb;
; #pragma unroll
;             for (int q = 0; q < 4; ++q) pre += a0[q] * w[q] + a1[q] * w[4 + q] + a2[q] * w[8 + q] + a3[q] * w[12 + q];
;             LA[(size_t)(row0 + row) * 512 + 64 * nb + lane] = log_sigmoid_f(pre) * 0.0625f;
;         }
;     }
.LBB0_245:
	v_mov_b32_e32 v42, s9
	ds_read_b128 v[22:25], v42
	ds_read_b128 v[26:29], v42 offset:16
	ds_read_b128 v[30:33], v42 offset:32
	ds_read_b128 v[34:37], v42 offset:48
	s_mov_b32 s10, 0x2e500000
	s_addk_i32 s9, 0x100
	s_waitcnt lgkmcnt(2)
	v_pk_mul_f32 v[26:27], v[10:11], v[26:27]
	s_nop 0
	v_pk_fma_f32 v[22:23], v[6:7], v[22:23], v[26:27]
	s_waitcnt lgkmcnt(1)
	v_pk_fma_f32 v[22:23], v[14:15], v[30:31], v[22:23]
	s_waitcnt lgkmcnt(0)
	v_pk_fma_f32 v[22:23], v[18:19], v[34:35], v[22:23]
	s_nop 0
	v_add_f32_e32 v22, v3, v22
	v_add_f32_e32 v26, v23, v22
	v_pk_mul_f32 v[22:23], v[12:13], v[28:29]
	s_nop 0
	v_pk_fma_f32 v[22:23], v[8:9], v[24:25], v[22:23]
	s_nop 0
	v_pk_fma_f32 v[22:23], v[16:17], v[32:33], v[22:23]
	s_nop 0
	v_pk_fma_f32 v[22:23], v[20:21], v[36:37], v[22:23]
	s_nop 0
	v_add_f32_e32 v22, v22, v26
	v_add_f32_e32 v22, v23, v22
	v_min_f32_e32 v23, 0, v22
	v_mul_f32_e64 v22, |v22|, s90
	v_exp_f32_e32 v22, v22
	s_nop 0
	v_add_f32_e32 v22, 1.0, v22
	v_log_f32_e32 v22, v22
	s_nop 0
	v_fmac_f32_e32 v23, 0xbf317218, v22
	v_mul_f32_e32 v24, 0x3d800000, v23
	v_lshl_add_u64 v[22:23], v[4:5], 0, s[0:1]
	v_add_co_u32_e32 v38, vcc, s10, v22
	s_mov_b32 s10, 0x2e501000
	s_nop 0
	v_addc_co_u32_e32 v39, vcc, 0, v23, vcc
	v_add_co_u32_e32 v40, vcc, s10, v22
	s_add_u32 s0, s0, 0x2000
	s_nop 0
	v_addc_co_u32_e32 v41, vcc, 0, v23, vcc
	global_store_dword v[40:41], v24, off offset:-4096
	ds_read_b128 v[22:25], v42 offset:64
	ds_read_b128 v[26:29], v42 offset:80
	ds_read_b128 v[30:33], v42 offset:96
	ds_read_b128 v[34:37], v42 offset:112
	s_addc_u32 s1, s1, 0
	s_cmpk_eq_u32 s0, 0x8000
	s_waitcnt lgkmcnt(2)
	v_pk_mul_f32 v[26:27], v[10:11], v[26:27]
	s_nop 0
	v_pk_fma_f32 v[22:23], v[6:7], v[22:23], v[26:27]
	s_waitcnt lgkmcnt(1)
	v_pk_fma_f32 v[22:23], v[14:15], v[30:31], v[22:23]
	s_waitcnt lgkmcnt(0)
	v_pk_fma_f32 v[22:23], v[18:19], v[34:35], v[22:23]
	s_nop 0
	v_add_f32_e32 v22, v3, v22
	v_add_f32_e32 v26, v23, v22
	v_pk_mul_f32 v[22:23], v[12:13], v[28:29]
	s_nop 0
	v_pk_fma_f32 v[22:23], v[8:9], v[24:25], v[22:23]
	s_nop 0
	v_pk_fma_f32 v[22:23], v[16:17], v[32:33], v[22:23]
	s_nop 0
	v_pk_fma_f32 v[22:23], v[20:21], v[36:37], v[22:23]
	s_nop 0
	v_add_f32_e32 v22, v22, v26
	v_add_f32_e32 v22, v23, v22
	v_min_f32_e32 v23, 0, v22
	v_mul_f32_e64 v22, |v22|, s90
	v_exp_f32_e32 v22, v22
	s_nop 0
	v_add_f32_e32 v22, 1.0, v22
	v_log_f32_e32 v22, v22
	s_nop 0
	v_fmac_f32_e32 v23, 0xbf317218, v22
	v_mul_f32_e32 v22, 0x3d800000, v23
	global_store_dword v[38:39], v22, off offset:2048
	ds_read_b128 v[22:25], v42 offset:128
	ds_read_b128 v[26:29], v42 offset:144
	ds_read_b128 v[30:33], v42 offset:160
	ds_read_b128 v[34:37], v42 offset:176
	s_waitcnt lgkmcnt(2)
	v_pk_mul_f32 v[26:27], v[10:11], v[26:27]
	s_nop 0
	v_pk_fma_f32 v[22:23], v[6:7], v[22:23], v[26:27]
	s_waitcnt lgkmcnt(1)
	v_pk_fma_f32 v[22:23], v[14:15], v[30:31], v[22:23]
	s_waitcnt lgkmcnt(0)
	v_pk_fma_f32 v[22:23], v[18:19], v[34:35], v[22:23]
	s_nop 0
	v_add_f32_e32 v22, v3, v22
	v_add_f32_e32 v26, v23, v22
	v_pk_mul_f32 v[22:23], v[12:13], v[28:29]
	s_nop 0
	v_pk_fma_f32 v[22:23], v[8:9], v[24:25], v[22:23]
	s_nop 0
	v_pk_fma_f32 v[22:23], v[16:17], v[32:33], v[22:23]
	s_nop 0
	v_pk_fma_f32 v[22:23], v[20:21], v[36:37], v[22:23]
	s_nop 0
	v_add_f32_e32 v22, v22, v26
	v_add_f32_e32 v22, v23, v22
	v_min_f32_e32 v23, 0, v22
	v_mul_f32_e64 v22, |v22|, s90
	v_exp_f32_e32 v22, v22
	s_nop 0
	v_add_f32_e32 v22, 1.0, v22
	v_log_f32_e32 v22, v22
	s_nop 0
	v_fmac_f32_e32 v23, 0xbf317218, v22
	v_mul_f32_e32 v22, 0x3d800000, v23
	global_store_dword v[40:41], v22, off
	ds_read_b128 v[22:25], v42 offset:192
	ds_read_b128 v[26:29], v42 offset:208
	ds_read_b128 v[30:33], v42 offset:224
	ds_read_b128 v[34:37], v42 offset:240
	s_waitcnt lgkmcnt(2)
	v_pk_mul_f32 v[26:27], v[10:11], v[26:27]
	s_nop 0
	v_pk_fma_f32 v[22:23], v[6:7], v[22:23], v[26:27]
	s_waitcnt lgkmcnt(1)
	v_pk_fma_f32 v[22:23], v[14:15], v[30:31], v[22:23]
	s_waitcnt lgkmcnt(0)
	v_pk_fma_f32 v[22:23], v[18:19], v[34:35], v[22:23]
	s_nop 0
	v_add_f32_e32 v22, v3, v22
	v_add_f32_e32 v26, v23, v22
	v_pk_mul_f32 v[22:23], v[12:13], v[28:29]
	s_nop 0
	v_pk_fma_f32 v[22:23], v[8:9], v[24:25], v[22:23]
	s_nop 0
	v_pk_fma_f32 v[22:23], v[16:17], v[32:33], v[22:23]
	s_nop 0
	v_pk_fma_f32 v[22:23], v[20:21], v[36:37], v[22:23]
	s_nop 0
	v_add_f32_e32 v22, v22, v26
	v_add_f32_e32 v22, v23, v22
	v_min_f32_e32 v23, 0, v22
	v_mul_f32_e64 v22, |v22|, s90
	v_exp_f32_e32 v22, v22
	s_nop 0
	v_add_f32_e32 v22, 1.0, v22
	v_log_f32_e32 v22, v22
	s_nop 0
	v_fmac_f32_e32 v23, 0xbf317218, v22
	v_mul_f32_e32 v22, 0x3d800000, v23
	global_store_dword v[40:41], v22, off offset:2048
	s_cbranch_scc0 .LBB0_245
	s_add_i32 s8, s8, 1
	s_cmp_eq_u32 s8, s101
	v_lshl_add_u64 v[4:5], v[4:5], 0, s[86:87]
	s_cbranch_scc0 .LBB0_244
	s_waitcnt lgkmcnt(0)

; __global__ void __launch_bounds__(NTHREADS, 2) hybrid_fwd(Args Aval) {
	.amdhsa_kernel _Z10hybrid_fwd4Args
		.amdhsa_group_segment_fixed_size 0
		.amdhsa_private_segment_fixed_size 0
		.amdhsa_kernarg_size 536
		.amdhsa_user_sgpr_count 2
		.amdhsa_user_sgpr_dispatch_ptr 0
		.amdhsa_user_sgpr_queue_ptr 0
		.amdhsa_user_sgpr_kernarg_segment_ptr 1
		.amdhsa_user_sgpr_dispatch_id 0
		.amdhsa_user_sgpr_kernarg_preload_length 0
		.amdhsa_user_sgpr_kernarg_preload_offset 0
		.amdhsa_user_sgpr_private_segment_size 0
		.amdhsa_uses_dynamic_stack 0
		.amdhsa_enable_private_segment 0
		.amdhsa_system_sgpr_workgroup_id_x 1
		.amdhsa_system_sgpr_workgroup_id_y 0
		.amdhsa_system_sgpr_workgroup_id_z 0
		.amdhsa_system_sgpr_workgroup_info 0
		.amdhsa_system_vgpr_workitem_id 0
		.amdhsa_next_free_vgpr 251
		.amdhsa_next_free_sgpr 102
		.amdhsa_accum_offset 252
		.amdhsa_reserve_vcc 1
		.amdhsa_float_round_mode_32 0
		.amdhsa_float_round_mode_16_64 0
		.amdhsa_float_denorm_mode_32 3
		.amdhsa_float_denorm_mode_16_64 3
		.amdhsa_dx10_clamp 1
		.amdhsa_ieee_mode 1
		.amdhsa_fp16_overflow 0
		.amdhsa_tg_split 0
		.amdhsa_exception_fp_ieee_invalid_op 0
		.amdhsa_exception_fp_denorm_src 0
		.amdhsa_exception_fp_ieee_div_zero 0
		.amdhsa_exception_fp_ieee_overflow 0
		.amdhsa_exception_fp_ieee_underflow 0
		.amdhsa_exception_fp_ieee_inexact 0
		.amdhsa_exception_int_div_zero 0
	.end_amdhsa_kernel

; __global__ void __launch_bounds__(NTHREADS, 2) hybrid_fwd(Args Aval) {
amdhsa.kernels:
  - .agpr_count:     0
    .args:
      - .offset:         0
        .size:           280
        .value_kind:     by_value
      - .offset:         280
        .size:           4
        .value_kind:     hidden_block_count_x
      - .offset:         284
        .size:           4
        .value_kind:     hidden_block_count_y
      - .offset:         288
        .size:           4
        .value_kind:     hidden_block_count_z
      - .offset:         292
        .size:           2
        .value_kind:     hidden_group_size_x
      - .offset:         294
        .size:           2
        .value_kind:     hidden_group_size_y
      - .offset:         296
        .size:           2
        .value_kind:     hidden_group_size_z
      - .offset:         298
        .size:           2
        .value_kind:     hidden_remainder_x
      - .offset:         300
        .size:           2
        .value_kind:     hidden_remainder_y
      - .offset:         302
        .size:           2
        .value_kind:     hidden_remainder_z
      - .offset:         320
        .size:           8
        .value_kind:     hidden_global_offset_x
      - .offset:         328
        .size:           8
        .value_kind:     hidden_global_offset_y
      - .offset:         336
        .size:           8
        .value_kind:     hidden_global_offset_z
      - .offset:         344
        .size:           2
        .value_kind:     hidden_grid_dims
      - .offset:         400
        .size:           4
        .value_kind:     hidden_dynamic_lds_size
    .group_segment_fixed_size: 0
    .kernarg_segment_align: 8
    .kernarg_segment_size: 536
    .language:       OpenCL C
    .language_version:
      - 2
      - 0
    .max_flat_workgroup_size: 512
    .name:           _Z10hybrid_fwd4Args
    .private_segment_fixed_size: 0
    .sgpr_count:     108
    .sgpr_spill_count: 12
    .symbol:         _Z10hybrid_fwd4Args.kd
    .uniform_work_group_size: 1
    .uses_dynamic_stack: false
    .vgpr_count:     251
    .vgpr_spill_count: 0
    .wavefront_size: 64
